# non-temporal hint on the read-once epilogue side loads of the merge GEMM (gates) and the down GEMM (residual)
# speedup vs baseline: 1.0010x; 1.0010x over previous
.LBB0_807:
	v_add_u32_e32 v212, s8, v227
	v_ashrrev_i32_e32 v213, 31, v212
	v_add_u32_e32 v210, s4, v229
	v_lshlrev_b64 v[128:129], 12, v[212:213]
	v_lshl_add_u64 v[128:129], s[24:25], 0, v[128:129]
	v_ashrrev_i32_e32 v211, 31, v210
	v_lshl_add_u64 v[128:129], v[210:211], 1, v[128:129]
	global_load_dwordx4 v[188:191], v[128:129], off offset:2048 nt
	s_cmp_eq_u32 s2, 0
	s_cselect_b64 s[4:5], -1, 0
	s_cmp_lg_u32 s2, 0
	s_cselect_b64 s[54:55], -1, 0
	v_mov_b32_e32 v164, 0
	s_and_b64 vcc, exec, s[54:55]
	v_mov_b32_e32 v184, 0
	v_mov_b32_e32 v185, 0
	v_mov_b32_e32 v186, 0
	v_mov_b32_e32 v187, 0
	s_cbranch_vccnz .LBB0_809
	global_load_dwordx4 v[184:187], v[128:129], off nt
.LBB0_809:
	global_load_dwordx4 v[180:183], v[128:129], off offset:2304 nt
	v_cndmask_b32_e64 v130, 0, 1, s[4:5]
	v_cmp_ne_u32_e64 s[8:9], 1, v130
	s_andn2_b64 vcc, exec, s[4:5]
	v_mov_b32_e32 v176, 0
	v_mov_b32_e32 v177, 0
	v_mov_b32_e32 v178, 0
	v_mov_b32_e32 v179, 0
	s_cbranch_vccnz .LBB0_811
	global_load_dwordx4 v[176:179], v[128:129], off offset:256 nt
.LBB0_811:
	v_add_u32_e32 v218, 16, v212
	v_ashrrev_i32_e32 v219, 31, v218
	v_lshlrev_b64 v[128:129], 12, v[218:219]
	v_lshl_add_u64 v[128:129], s[24:25], 0, v[128:129]
	v_lshl_add_u64 v[128:129], v[210:211], 1, v[128:129]
	global_load_dwordx4 v[172:175], v[128:129], off offset:2048 nt
	s_and_b64 vcc, exec, s[8:9]
	v_mov_b32_e32 v165, 0
	v_mov_b32_e32 v166, 0
	v_mov_b32_e32 v167, 0
	s_cbranch_vccnz .LBB0_813
	global_load_dwordx4 v[164:167], v[128:129], off nt
.LBB0_813:
	global_load_dwordx4 v[168:171], v[128:129], off offset:2304 nt
	v_mov_b32_e32 v148, 0
	s_and_b64 vcc, exec, s[8:9]
	v_mov_b32_e32 v160, 0
	v_mov_b32_e32 v161, 0
	v_mov_b32_e32 v162, 0
	v_mov_b32_e32 v163, 0
	s_cbranch_vccnz .LBB0_815
	global_load_dwordx4 v[160:163], v[128:129], off offset:256 nt
.LBB0_815:
	v_add_u32_e32 v216, 32, v212
	v_ashrrev_i32_e32 v217, 31, v216
	v_lshlrev_b64 v[128:129], 12, v[216:217]
	v_lshl_add_u64 v[128:129], s[24:25], 0, v[128:129]
	v_lshl_add_u64 v[128:129], v[210:211], 1, v[128:129]
	global_load_dwordx4 v[156:159], v[128:129], off offset:2048 nt
	s_and_b64 vcc, exec, s[8:9]
	v_mov_b32_e32 v149, 0
	v_mov_b32_e32 v150, 0
	v_mov_b32_e32 v151, 0
	s_cbranch_vccnz .LBB0_817
	global_load_dwordx4 v[148:151], v[128:129], off nt
.LBB0_817:
	global_load_dwordx4 v[152:155], v[128:129], off offset:2304 nt
	v_mov_b32_e32 v132, 0
	s_and_b64 vcc, exec, s[8:9]
	v_mov_b32_e32 v144, 0
	v_mov_b32_e32 v145, 0
	v_mov_b32_e32 v146, 0
	v_mov_b32_e32 v147, 0
	s_cbranch_vccnz .LBB0_819
	global_load_dwordx4 v[144:147], v[128:129], off offset:256 nt
.LBB0_819:
	v_add_u32_e32 v214, 48, v212
	v_ashrrev_i32_e32 v215, 31, v214
	v_lshlrev_b64 v[128:129], 12, v[214:215]
	v_lshl_add_u64 v[128:129], s[24:25], 0, v[128:129]
	v_lshl_add_u64 v[220:221], v[210:211], 1, v[128:129]
	global_load_dwordx4 v[140:143], v[220:221], off offset:2048 nt
	s_and_b64 vcc, exec, s[8:9]
	v_mov_b32_e32 v133, 0
	v_mov_b32_e32 v134, 0
	v_mov_b32_e32 v135, 0
	s_cbranch_vccnz .LBB0_821
	global_load_dwordx4 v[132:135], v[220:221], off nt
.LBB0_821:
	global_load_dwordx4 v[136:139], v[220:221], off offset:2304 nt
	v_mov_b32_e32 v128, 0
	s_and_b64 vcc, exec, s[8:9]
	v_mov_b32_e32 v129, 0
	v_mov_b32_e32 v130, 0
	v_mov_b32_e32 v131, 0
	s_cbranch_vccnz .LBB0_823
	global_load_dwordx4 v[128:131], v[220:221], off offset:256 nt

.LBB0_855:
	v_add_u32_e32 v218, 0x80, v212
	v_ashrrev_i32_e32 v219, 31, v218
	v_lshlrev_b64 v[128:129], 12, v[218:219]
	v_lshl_add_u64 v[128:129], s[24:25], 0, v[128:129]
	v_lshl_add_u64 v[128:129], v[210:211], 1, v[128:129]
	global_load_dwordx4 v[188:191], v[128:129], off offset:2048 nt
	v_mov_b32_e32 v172, 0
	s_and_b64 vcc, exec, s[8:9]
	v_mov_b32_e32 v184, 0
	v_mov_b32_e32 v185, 0
	v_mov_b32_e32 v186, 0
	v_mov_b32_e32 v187, 0
	s_cbranch_vccnz .LBB0_857
	global_load_dwordx4 v[184:187], v[128:129], off nt
.LBB0_857:
	global_load_dwordx4 v[180:183], v[128:129], off offset:2304 nt
	s_and_b64 vcc, exec, s[8:9]
	v_mov_b32_e32 v173, 0
	v_mov_b32_e32 v174, 0
	v_mov_b32_e32 v175, 0
	s_cbranch_vccnz .LBB0_859
	global_load_dwordx4 v[172:175], v[128:129], off offset:256 nt
.LBB0_859:
	v_add_u32_e32 v216, 0x90, v212
	v_ashrrev_i32_e32 v217, 31, v216
	v_lshlrev_b64 v[128:129], 12, v[216:217]
	v_lshl_add_u64 v[128:129], s[24:25], 0, v[128:129]
	v_lshl_add_u64 v[128:129], v[210:211], 1, v[128:129]
	global_load_dwordx4 v[176:179], v[128:129], off offset:2048 nt
	v_mov_b32_e32 v156, 0
	s_and_b64 vcc, exec, s[8:9]
	v_mov_b32_e32 v168, 0
	v_mov_b32_e32 v169, 0
	v_mov_b32_e32 v170, 0
	v_mov_b32_e32 v171, 0
	s_cbranch_vccnz .LBB0_861
	global_load_dwordx4 v[168:171], v[128:129], off nt
.LBB0_861:
	global_load_dwordx4 v[164:167], v[128:129], off offset:2304 nt
	s_and_b64 vcc, exec, s[8:9]
	v_mov_b32_e32 v157, 0
	v_mov_b32_e32 v158, 0
	v_mov_b32_e32 v159, 0
	s_cbranch_vccnz .LBB0_863
	global_load_dwordx4 v[156:159], v[128:129], off offset:256 nt
.LBB0_863:
	v_add_u32_e32 v214, 0xa0, v212
	v_ashrrev_i32_e32 v215, 31, v214
	v_lshlrev_b64 v[128:129], 12, v[214:215]
	v_lshl_add_u64 v[128:129], s[24:25], 0, v[128:129]
	v_lshl_add_u64 v[128:129], v[210:211], 1, v[128:129]
	global_load_dwordx4 v[160:163], v[128:129], off offset:2048 nt
	v_mov_b32_e32 v140, 0
	s_and_b64 vcc, exec, s[8:9]
	v_mov_b32_e32 v152, 0
	v_mov_b32_e32 v153, 0
	v_mov_b32_e32 v154, 0
	v_mov_b32_e32 v155, 0
	s_cbranch_vccnz .LBB0_865
	global_load_dwordx4 v[152:155], v[128:129], off nt
.LBB0_865:
	global_load_dwordx4 v[148:151], v[128:129], off offset:2304 nt
	s_and_b64 vcc, exec, s[8:9]
	v_mov_b32_e32 v141, 0
	v_mov_b32_e32 v142, 0
	v_mov_b32_e32 v143, 0
	s_cbranch_vccnz .LBB0_867
	global_load_dwordx4 v[140:143], v[128:129], off offset:256 nt
.LBB0_867:
	v_add_u32_e32 v212, 0xb0, v212
	v_ashrrev_i32_e32 v213, 31, v212
	v_lshlrev_b64 v[128:129], 12, v[212:213]
	v_lshl_add_u64 v[128:129], s[24:25], 0, v[128:129]
	v_lshl_add_u64 v[220:221], v[210:211], 1, v[128:129]
	global_load_dwordx4 v[144:147], v[220:221], off offset:2048 nt
	v_mov_b32_e32 v128, 0
	s_and_b64 vcc, exec, s[8:9]
	v_mov_b32_e32 v136, 0
	v_mov_b32_e32 v137, 0
	v_mov_b32_e32 v138, 0
	v_mov_b32_e32 v139, 0
	s_cbranch_vccnz .LBB0_869
	global_load_dwordx4 v[136:139], v[220:221], off nt
.LBB0_869:
	global_load_dwordx4 v[132:135], v[220:221], off offset:2304 nt
	s_and_b64 vcc, exec, s[8:9]
	v_mov_b32_e32 v129, 0
	v_mov_b32_e32 v130, 0
	v_mov_b32_e32 v131, 0
	s_cbranch_vccnz .LBB0_871
	global_load_dwordx4 v[128:131], v[220:221], off offset:256 nt

.LBB0_1180:
	v_add_u32_e32 v164, s49, v168
	v_add_u32_e32 v128, s50, v170
	v_ashrrev_i32_e32 v165, 31, v164
	v_ashrrev_i32_e32 v129, 31, v128
	v_lshlrev_b64 v[190:191], 11, v[164:165]
	v_lshl_add_u64 v[130:131], s[22:23], 0, v[190:191]
	v_lshlrev_b64 v[162:163], 1, v[128:129]
	v_lshl_add_u64 v[130:131], v[130:131], 0, v[162:163]
	global_load_dwordx4 v[174:177], v[130:131], off nt
	global_load_dwordx4 v[178:181], v[130:131], off offset:256 nt
	v_add_u32_e32 v130, 16, v164
	v_ashrrev_i32_e32 v131, 31, v130
	v_lshlrev_b64 v[210:211], 11, v[130:131]
	v_lshl_add_u64 v[130:131], s[22:23], 0, v[210:211]
	v_lshl_add_u64 v[130:131], v[130:131], 0, v[162:163]
	global_load_dwordx4 v[182:185], v[130:131], off nt
	global_load_dwordx4 v[186:189], v[130:131], off offset:256 nt
	v_add_u32_e32 v130, 32, v164
	v_ashrrev_i32_e32 v131, 31, v130
	v_lshlrev_b64 v[212:213], 11, v[130:131]
	v_lshl_add_u64 v[130:131], s[22:23], 0, v[212:213]
	s_ashr_i32 s26, s49, 11
	v_lshl_add_u64 v[130:131], v[130:131], 0, v[162:163]
	s_mul_i32 s26, s26, 6
	global_load_dwordx4 v[194:197], v[130:131], off nt
	global_load_dwordx4 v[198:201], v[130:131], off offset:256 nt
	v_add_u32_e32 v130, 48, v164
	s_ashr_i32 s27, s26, 31
	v_ashrrev_i32_e32 v131, 31, v130
	s_lshl_b64 s[26:27], s[26:27], 12
	v_lshlrev_b64 v[166:167], 11, v[130:131]
	s_add_u32 s26, s39, s26
	v_lshl_add_u64 v[130:131], s[22:23], 0, v[166:167]
	s_addc_u32 s27, s40, s27
	v_lshl_add_u64 v[130:131], v[130:131], 0, v[162:163]
	v_lshl_add_u64 v[128:129], v[128:129], 2, s[26:27]
	global_load_dwordx4 v[202:205], v[130:131], off nt
	global_load_dwordx4 v[206:209], v[130:131], off offset:256 nt
	global_load_dwordx4 v[140:143], v[128:129], off nt
	global_load_dwordx4 v[136:139], v[128:129], off offset:16 nt
	global_load_dwordx4 v[132:135], v[128:129], off offset:512 nt
	s_nop 0
	global_load_dwordx4 v[128:131], v[128:129], off offset:528 nt
	s_andn2_b64 vcc, exec, s[0:1]
	s_mov_b64 s[0:1], -1
	s_waitcnt vmcnt(0)
	v_lshlrev_b32_e32 v214, 16, v174
	v_and_b32_e32 v215, 0xffff0000, v174
	v_lshlrev_b32_e32 v174, 16, v175
	v_and_b32_e32 v175, 0xffff0000, v175
	v_lshlrev_b32_e32 v216, 16, v176
	v_and_b32_e32 v217, 0xffff0000, v176
	v_lshlrev_b32_e32 v176, 16, v177
	v_and_b32_e32 v177, 0xffff0000, v177
	v_lshlrev_b32_e32 v218, 16, v178
	v_and_b32_e32 v219, 0xffff0000, v178
	v_lshlrev_b32_e32 v178, 16, v179
	v_and_b32_e32 v179, 0xffff0000, v179
	v_lshlrev_b32_e32 v220, 16, v180
	v_and_b32_e32 v221, 0xffff0000, v180
	v_lshlrev_b32_e32 v180, 16, v181
	v_and_b32_e32 v181, 0xffff0000, v181
	v_lshlrev_b32_e32 v222, 16, v182
	v_and_b32_e32 v223, 0xffff0000, v182
	v_lshlrev_b32_e32 v182, 16, v183
	v_and_b32_e32 v183, 0xffff0000, v183
	v_lshlrev_b32_e32 v224, 16, v184
	v_and_b32_e32 v225, 0xffff0000, v184
	v_lshlrev_b32_e32 v184, 16, v185
	v_and_b32_e32 v185, 0xffff0000, v185
	v_pk_fma_f32 v[124:125], v[124:125], v[140:141], v[214:215]
	v_pk_fma_f32 v[126:127], v[126:127], v[142:143], v[174:175]
	v_pk_fma_f32 v[174:175], v[122:123], v[138:139], v[176:177]
	v_pk_fma_f32 v[122:123], v[120:121], v[136:137], v[216:217]
	v_cvt_pk_bf16_f32 v120, v124, v125
	v_lshl_add_u64 v[124:125], s[18:19], 0, v[190:191]
	v_cvt_pk_bf16_f32 v121, v126, v127
	v_cvt_pk_bf16_f32 v122, v122, v123
	v_cvt_pk_bf16_f32 v123, v174, v175
	v_lshl_add_u64 v[124:125], v[124:125], 0, v[162:163]
	global_store_dwordx4 v[124:125], v[120:123], off
	v_pk_fma_f32 v[118:119], v[118:119], v[134:135], v[178:179]
	v_pk_fma_f32 v[116:117], v[116:117], v[132:133], v[218:219]
	v_pk_fma_f32 v[120:121], v[110:111], v[130:131], v[180:181]
	v_pk_fma_f32 v[110:111], v[108:109], v[128:129], v[220:221]
	v_cvt_pk_bf16_f32 v108, v116, v117
	v_cvt_pk_bf16_f32 v109, v118, v119
	v_cvt_pk_bf16_f32 v110, v110, v111
	v_cvt_pk_bf16_f32 v111, v120, v121
	global_store_dwordx4 v[124:125], v[108:111], off offset:256
	v_lshlrev_b32_e32 v228, 16, v186
	v_and_b32_e32 v229, 0xffff0000, v186
	v_pk_fma_f32 v[108:109], v[114:115], v[142:143], v[182:183]
	v_pk_fma_f32 v[110:111], v[112:113], v[140:141], v[222:223]
	v_pk_fma_f32 v[112:113], v[106:107], v[138:139], v[184:185]
	v_pk_fma_f32 v[106:107], v[104:105], v[136:137], v[224:225]
	v_cvt_pk_bf16_f32 v105, v108, v109
	v_lshl_add_u64 v[108:109], s[18:19], 0, v[210:211]
	v_lshlrev_b32_e32 v186, 16, v187
	v_and_b32_e32 v187, 0xffff0000, v187
	v_lshlrev_b32_e32 v230, 16, v188
	v_and_b32_e32 v231, 0xffff0000, v188
	v_lshlrev_b32_e32 v188, 16, v189
	v_and_b32_e32 v189, 0xffff0000, v189
	v_cvt_pk_bf16_f32 v104, v110, v111
	v_cvt_pk_bf16_f32 v106, v106, v107
	v_cvt_pk_bf16_f32 v107, v112, v113
	v_lshl_add_u64 v[108:109], v[108:109], 0, v[162:163]
	global_store_dwordx4 v[108:109], v[104:107], off
	v_pk_fma_f32 v[102:103], v[102:103], v[134:135], v[186:187]
	v_pk_fma_f32 v[100:101], v[100:101], v[132:133], v[228:229]
	v_pk_fma_f32 v[104:105], v[94:95], v[130:131], v[188:189]
	v_pk_fma_f32 v[94:95], v[92:93], v[128:129], v[230:231]
	v_lshlrev_b32_e32 v232, 16, v194
	v_and_b32_e32 v233, 0xffff0000, v194
	v_lshlrev_b32_e32 v194, 16, v195
	v_and_b32_e32 v195, 0xffff0000, v195
	v_cvt_pk_bf16_f32 v92, v100, v101
	v_cvt_pk_bf16_f32 v93, v102, v103
	v_cvt_pk_bf16_f32 v94, v94, v95
	v_cvt_pk_bf16_f32 v95, v104, v105
	v_lshlrev_b32_e32 v234, 16, v196
	v_and_b32_e32 v235, 0xffff0000, v196
	v_lshlrev_b32_e32 v196, 16, v197
	v_and_b32_e32 v197, 0xffff0000, v197
	global_store_dwordx4 v[108:109], v[92:95], off offset:256
	v_lshlrev_b32_e32 v236, 16, v198
	v_and_b32_e32 v237, 0xffff0000, v198
	v_pk_fma_f32 v[92:93], v[98:99], v[142:143], v[194:195]
	v_pk_fma_f32 v[94:95], v[96:97], v[140:141], v[232:233]
	v_pk_fma_f32 v[96:97], v[90:91], v[138:139], v[196:197]
	v_pk_fma_f32 v[90:91], v[88:89], v[136:137], v[234:235]
	v_cvt_pk_bf16_f32 v89, v92, v93
	v_lshl_add_u64 v[92:93], s[18:19], 0, v[212:213]
	v_lshlrev_b32_e32 v198, 16, v199
	v_and_b32_e32 v199, 0xffff0000, v199
	v_lshlrev_b32_e32 v238, 16, v200
	v_and_b32_e32 v239, 0xffff0000, v200
	v_lshlrev_b32_e32 v200, 16, v201
	v_and_b32_e32 v201, 0xffff0000, v201
	v_cvt_pk_bf16_f32 v88, v94, v95
	v_cvt_pk_bf16_f32 v90, v90, v91
	v_cvt_pk_bf16_f32 v91, v96, v97
	v_lshl_add_u64 v[92:93], v[92:93], 0, v[162:163]
	global_store_dwordx4 v[92:93], v[88:91], off
	v_pk_fma_f32 v[86:87], v[86:87], v[134:135], v[198:199]
	v_pk_fma_f32 v[84:85], v[84:85], v[132:133], v[236:237]
	v_pk_fma_f32 v[88:89], v[78:79], v[130:131], v[200:201]
	v_pk_fma_f32 v[78:79], v[76:77], v[128:129], v[238:239]
	v_lshlrev_b32_e32 v240, 16, v202
	v_and_b32_e32 v241, 0xffff0000, v202
	v_lshlrev_b32_e32 v202, 16, v203
	v_and_b32_e32 v203, 0xffff0000, v203
	v_cvt_pk_bf16_f32 v76, v84, v85
	v_cvt_pk_bf16_f32 v77, v86, v87
	v_cvt_pk_bf16_f32 v78, v78, v79
	v_cvt_pk_bf16_f32 v79, v88, v89
	v_lshlrev_b32_e32 v242, 16, v204
	v_and_b32_e32 v243, 0xffff0000, v204
	v_lshlrev_b32_e32 v204, 16, v205
	v_and_b32_e32 v205, 0xffff0000, v205
	global_store_dwordx4 v[92:93], v[76:79], off offset:256
	v_lshlrev_b32_e32 v244, 16, v206
	v_and_b32_e32 v245, 0xffff0000, v206
	v_pk_fma_f32 v[76:77], v[82:83], v[142:143], v[202:203]
	v_pk_fma_f32 v[78:79], v[80:81], v[140:141], v[240:241]
	v_pk_fma_f32 v[80:81], v[74:75], v[138:139], v[204:205]
	v_pk_fma_f32 v[74:75], v[72:73], v[136:137], v[242:243]
	v_cvt_pk_bf16_f32 v73, v76, v77
	v_lshl_add_u64 v[76:77], s[18:19], 0, v[166:167]
	v_cvt_pk_bf16_f32 v72, v78, v79
	v_cvt_pk_bf16_f32 v74, v74, v75
	v_cvt_pk_bf16_f32 v75, v80, v81
	v_lshl_add_u64 v[76:77], v[76:77], 0, v[162:163]
	global_store_dwordx4 v[76:77], v[72:75], off
	v_lshlrev_b32_e32 v206, 16, v207
	v_and_b32_e32 v207, 0xffff0000, v207
	v_pk_fma_f32 v[74:75], v[68:69], v[132:133], v[244:245]
	v_add_u32_e32 v68, 0x80, v164
	v_ashrrev_i32_e32 v69, 31, v68
	v_lshlrev_b32_e32 v246, 16, v208
	v_and_b32_e32 v247, 0xffff0000, v208
	v_lshlrev_b32_e32 v208, 16, v209
	v_and_b32_e32 v209, 0xffff0000, v209
	v_lshlrev_b64 v[100:101], 11, v[68:69]
	v_pk_fma_f32 v[72:73], v[70:71], v[134:135], v[206:207]
	v_lshl_add_u64 v[68:69], s[22:23], 0, v[100:101]
	v_pk_fma_f32 v[80:81], v[66:67], v[130:131], v[208:209]
	v_pk_fma_f32 v[66:67], v[64:65], v[128:129], v[246:247]
	v_lshl_add_u64 v[78:79], v[68:69], 0, v[162:163]
	v_cvt_pk_bf16_f32 v64, v74, v75
	v_cvt_pk_bf16_f32 v65, v72, v73
	v_cvt_pk_bf16_f32 v66, v66, v67
	v_cvt_pk_bf16_f32 v67, v80, v81
	global_load_dwordx4 v[68:71], v[78:79], off nt
	s_nop 0
	global_store_dwordx4 v[76:77], v[64:67], off offset:256
	global_load_dwordx4 v[72:75], v[78:79], off offset:256 nt
	s_waitcnt vmcnt(2)
	v_lshlrev_b32_e32 v104, 16, v68
	v_add_u32_e32 v64, 0x90, v164
	v_ashrrev_i32_e32 v65, 31, v64
	v_lshlrev_b64 v[66:67], 11, v[64:65]
	v_lshl_add_u64 v[64:65], s[22:23], 0, v[66:67]
	v_lshl_add_u64 v[64:65], v[64:65], 0, v[162:163]
	global_load_dwordx4 v[76:79], v[64:65], off nt
	global_load_dwordx4 v[80:83], v[64:65], off offset:256 nt
	v_add_u32_e32 v64, 0xa0, v164
	v_ashrrev_i32_e32 v65, 31, v64
	v_lshlrev_b64 v[102:103], 11, v[64:65]
	v_lshl_add_u64 v[64:65], s[22:23], 0, v[102:103]
	v_lshl_add_u64 v[64:65], v[64:65], 0, v[162:163]
	global_load_dwordx4 v[84:87], v[64:65], off nt
	global_load_dwordx4 v[88:91], v[64:65], off offset:256 nt
	v_add_u32_e32 v64, 0xb0, v164
	v_ashrrev_i32_e32 v65, 31, v64
	v_lshlrev_b64 v[64:65], 11, v[64:65]
	v_lshl_add_u64 v[92:93], s[22:23], 0, v[64:65]
	v_lshl_add_u64 v[96:97], v[92:93], 0, v[162:163]
	global_load_dwordx4 v[92:95], v[96:97], off nt
	s_nop 0
	global_load_dwordx4 v[96:99], v[96:97], off offset:256 nt
	v_and_b32_e32 v105, 0xffff0000, v68
	v_lshlrev_b32_e32 v68, 16, v69
	v_and_b32_e32 v69, 0xffff0000, v69
	v_lshlrev_b32_e32 v106, 16, v70
	v_and_b32_e32 v107, 0xffff0000, v70
	v_lshlrev_b32_e32 v70, 16, v71
	v_and_b32_e32 v71, 0xffff0000, v71
	v_pk_fma_f32 v[60:61], v[60:61], v[140:141], v[104:105]
	v_pk_fma_f32 v[62:63], v[62:63], v[142:143], v[68:69]
	v_pk_fma_f32 v[68:69], v[58:59], v[138:139], v[70:71]
	v_pk_fma_f32 v[58:59], v[56:57], v[136:137], v[106:107]
	v_cvt_pk_bf16_f32 v56, v60, v61
	v_lshl_add_u64 v[60:61], s[18:19], 0, v[100:101]
	s_waitcnt vmcnt(6)
	v_lshlrev_b32_e32 v108, 16, v72
	v_and_b32_e32 v109, 0xffff0000, v72
	v_lshlrev_b32_e32 v72, 16, v73
	v_and_b32_e32 v73, 0xffff0000, v73
	v_lshlrev_b32_e32 v110, 16, v74
	v_and_b32_e32 v111, 0xffff0000, v74
	v_lshlrev_b32_e32 v74, 16, v75
	v_and_b32_e32 v75, 0xffff0000, v75
	v_cvt_pk_bf16_f32 v57, v62, v63
	v_cvt_pk_bf16_f32 v58, v58, v59
	v_cvt_pk_bf16_f32 v59, v68, v69
	v_lshl_add_u64 v[60:61], v[60:61], 0, v[162:163]
	global_store_dwordx4 v[60:61], v[56:59], off
	v_pk_fma_f32 v[54:55], v[54:55], v[134:135], v[72:73]
	v_pk_fma_f32 v[52:53], v[52:53], v[132:133], v[108:109]
	v_pk_fma_f32 v[56:57], v[38:39], v[130:131], v[74:75]
	v_pk_fma_f32 v[38:39], v[36:37], v[128:129], v[110:111]
	v_cvt_pk_bf16_f32 v36, v52, v53
	v_cvt_pk_bf16_f32 v37, v54, v55
	v_cvt_pk_bf16_f32 v38, v38, v39
	v_cvt_pk_bf16_f32 v39, v56, v57
	global_store_dwordx4 v[60:61], v[36:39], off offset:256
	s_waitcnt vmcnt(7)
	v_lshlrev_b32_e32 v112, 16, v76
	v_and_b32_e32 v113, 0xffff0000, v76
	v_lshlrev_b32_e32 v76, 16, v77
	v_and_b32_e32 v77, 0xffff0000, v77
	v_lshlrev_b32_e32 v114, 16, v78
	v_and_b32_e32 v115, 0xffff0000, v78
	v_lshlrev_b32_e32 v78, 16, v79
	v_and_b32_e32 v79, 0xffff0000, v79
	v_pk_fma_f32 v[36:37], v[50:51], v[142:143], v[76:77]
	v_pk_fma_f32 v[38:39], v[48:49], v[140:141], v[112:113]
	v_pk_fma_f32 v[48:49], v[34:35], v[138:139], v[78:79]
	v_pk_fma_f32 v[34:35], v[32:33], v[136:137], v[114:115]
	v_cvt_pk_bf16_f32 v33, v36, v37
	v_lshl_add_u64 v[36:37], s[18:19], 0, v[66:67]
	s_waitcnt vmcnt(6)
	v_lshlrev_b32_e32 v116, 16, v80
	v_and_b32_e32 v117, 0xffff0000, v80
	v_lshlrev_b32_e32 v80, 16, v81
	v_and_b32_e32 v81, 0xffff0000, v81
	v_lshlrev_b32_e32 v118, 16, v82
	v_and_b32_e32 v119, 0xffff0000, v82
	v_lshlrev_b32_e32 v82, 16, v83
	v_and_b32_e32 v83, 0xffff0000, v83
	v_cvt_pk_bf16_f32 v32, v38, v39
	v_cvt_pk_bf16_f32 v34, v34, v35
	v_cvt_pk_bf16_f32 v35, v48, v49
	v_lshl_add_u64 v[36:37], v[36:37], 0, v[162:163]
	global_store_dwordx4 v[36:37], v[32:35], off
	v_pk_fma_f32 v[22:23], v[22:23], v[134:135], v[80:81]
	v_pk_fma_f32 v[20:21], v[20:21], v[132:133], v[116:117]
	v_pk_fma_f32 v[32:33], v[10:11], v[130:131], v[82:83]
	v_pk_fma_f32 v[10:11], v[8:9], v[128:129], v[118:119]
	s_waitcnt vmcnt(6)
	v_lshlrev_b32_e32 v120, 16, v84
	v_and_b32_e32 v121, 0xffff0000, v84
	v_lshlrev_b32_e32 v84, 16, v85
	v_and_b32_e32 v85, 0xffff0000, v85
	v_lshlrev_b32_e32 v122, 16, v86
	v_and_b32_e32 v123, 0xffff0000, v86
	v_cvt_pk_bf16_f32 v8, v20, v21
	v_cvt_pk_bf16_f32 v9, v22, v23
	v_cvt_pk_bf16_f32 v10, v10, v11
	v_cvt_pk_bf16_f32 v11, v32, v33
	v_lshlrev_b32_e32 v86, 16, v87
	v_and_b32_e32 v87, 0xffff0000, v87
	global_store_dwordx4 v[36:37], v[8:11], off offset:256
	v_pk_fma_f32 v[12:13], v[12:13], v[136:137], v[122:123]
	v_pk_fma_f32 v[14:15], v[14:15], v[138:139], v[86:87]
	v_pk_fma_f32 v[10:11], v[18:19], v[142:143], v[84:85]
	v_pk_fma_f32 v[8:9], v[16:17], v[140:141], v[120:121]
	s_waitcnt vmcnt(6)
	v_lshlrev_b32_e32 v124, 16, v88
	v_cvt_pk_bf16_f32 v8, v8, v9
	v_cvt_pk_bf16_f32 v9, v10, v11
	v_cvt_pk_bf16_f32 v10, v12, v13
	v_lshl_add_u64 v[12:13], s[18:19], 0, v[102:103]
	v_and_b32_e32 v125, 0xffff0000, v88
	v_lshlrev_b32_e32 v88, 16, v89
	v_and_b32_e32 v89, 0xffff0000, v89
	v_lshlrev_b32_e32 v126, 16, v90
	v_and_b32_e32 v127, 0xffff0000, v90
	v_lshlrev_b32_e32 v90, 16, v91
	v_and_b32_e32 v91, 0xffff0000, v91
	v_cvt_pk_bf16_f32 v11, v14, v15
	v_lshl_add_u64 v[12:13], v[12:13], 0, v[162:163]
	s_waitcnt vmcnt(5)
	v_lshlrev_b32_e32 v164, 16, v92
	v_and_b32_e32 v165, 0xffff0000, v92
	global_store_dwordx4 v[12:13], v[8:11], off
	v_pk_fma_f32 v[14:15], v[42:43], v[130:131], v[90:91]
	v_pk_fma_f32 v[16:17], v[40:41], v[128:129], v[126:127]
	v_pk_fma_f32 v[10:11], v[46:47], v[134:135], v[88:89]
	v_pk_fma_f32 v[8:9], v[44:45], v[132:133], v[124:125]
	v_lshlrev_b32_e32 v92, 16, v93
	v_and_b32_e32 v93, 0xffff0000, v93
	v_lshlrev_b32_e32 v166, 16, v94
	v_and_b32_e32 v167, 0xffff0000, v94
	v_lshlrev_b32_e32 v94, 16, v95
	v_and_b32_e32 v95, 0xffff0000, v95
	v_cvt_pk_bf16_f32 v8, v8, v9
	v_cvt_pk_bf16_f32 v9, v10, v11
	v_cvt_pk_bf16_f32 v10, v16, v17
	v_cvt_pk_bf16_f32 v11, v14, v15
	v_pk_fma_f32 v[4:5], v[4:5], v[140:141], v[164:165]
	global_store_dwordx4 v[12:13], v[8:11], off offset:256
	v_pk_fma_f32 v[6:7], v[6:7], v[142:143], v[92:93]
	s_waitcnt vmcnt(6)
	v_lshlrev_b32_e32 v174, 16, v96
	v_pk_fma_f32 v[8:9], v[2:3], v[138:139], v[94:95]
	v_pk_fma_f32 v[2:3], v[0:1], v[136:137], v[166:167]
	v_cvt_pk_bf16_f32 v0, v4, v5
	v_lshl_add_u64 v[4:5], s[18:19], 0, v[64:65]
	v_and_b32_e32 v175, 0xffff0000, v96
	v_lshlrev_b32_e32 v96, 16, v97
	v_and_b32_e32 v97, 0xffff0000, v97
	v_lshlrev_b32_e32 v176, 16, v98
	v_and_b32_e32 v177, 0xffff0000, v98
	v_lshlrev_b32_e32 v98, 16, v99
	v_and_b32_e32 v99, 0xffff0000, v99
	v_cvt_pk_bf16_f32 v1, v6, v7
	v_cvt_pk_bf16_f32 v2, v2, v3
	v_cvt_pk_bf16_f32 v3, v8, v9
	v_lshl_add_u64 v[4:5], v[4:5], 0, v[162:163]
	global_store_dwordx4 v[4:5], v[0:3], off
	v_pk_fma_f32 v[6:7], v[26:27], v[130:131], v[98:99]
	v_pk_fma_f32 v[8:9], v[24:25], v[128:129], v[176:177]
	v_pk_fma_f32 v[2:3], v[30:31], v[134:135], v[96:97]
	v_pk_fma_f32 v[0:1], v[28:29], v[132:133], v[174:175]
	s_nop 0
	v_cvt_pk_bf16_f32 v0, v0, v1
	v_cvt_pk_bf16_f32 v1, v2, v3
	v_cvt_pk_bf16_f32 v2, v8, v9
	v_cvt_pk_bf16_f32 v3, v6, v7
	global_store_dwordx4 v[4:5], v[0:3], off offset:256
	s_cbranch_vccnz .LBB0_1169
	s_andn2_b64 vcc, exec, s[8:9]
	s_cbranch_vccnz .LBB0_1168
	s_barrier
	s_branch .LBB0_1168
